# first-unit halo poll cadence s_sleep 8 -> 1; dead zeroing of the halo-copy registers removed
# speedup vs baseline: 1.0002x; 1.0002x over previous
;     __device__ __forceinline__ void operator()(const f32x4 (&acc)[2][2][4][2], const Unit& u, int wr, int wc, int fr, int fq) const {
;     ...
;             const int rowb = u.pm * 256 + ai * 128 + wr * 64;
;             const int blk = 4 * u.pm + 2 * ai + wr;
;             float rs[4];
; #pragma unroll
;             for (int m = 0; m < 4; ++m) rs[m] = rsqrtf(SS[rowb + 16 * m + fr] * (1.0f / D) + EPS);
; #pragma unroll
;             for (int n = 0; n < 2; ++n) {
;                 f32x4 cg[4];
; #pragma unroll
;                 for (int bj = 0; bj < 2; ++bj) {
;                     const int oc = (bj ? FF : 0) + 128 * u.pn + 32 * wc + 8 * fq + 4 * n;
;                     const int cgc = 256 * u.pn + 128 * bj + 32 * wc + 8 * fq + 4 * n;
;                     const f32x4 cw0 = *(const f32x4*)(convw + oc), cw1 = *(const f32x4*)(convw + FF2 + oc), cw2 = *(const f32x4*)(convw + 2 * FF2 + oc), cb = *(const f32x4*)(convb + oc);
;                     f32x4 v[4];
; #pragma unroll
;                     for (int m = 0; m < 4; ++m) v[m] = acc[ai][bj][m][n] * rs[m];
;                     f32x4 hv = (f32x4){0.f, 0.f, 0.f, 0.f};
.Lfe_begin:
	v_readlane_b32 s13, v236, 19
	s_lshl_b32 s77, s88, 8
	s_lshl_b32 s89, s12, 7
	s_lshl_b32 s75, s88, 2
	s_add_i32 s75, s75, s73
	s_add_i32 s77, s77, s13
	v_add_u32_e32 v246, s77, v153
	v_add_u32_e32 v247, s13, v153
	v_lshlrev_b32_e32 v247, 2, v247
	v_add_u32_e32 v247, 0x22000, v247
	ds_read2_b32 v[238:239], v247 offset0:0 offset1:16
	ds_read2_b32 v[240:241], v247 offset0:32 offset1:48
	ds_read2_b32 v[242:243], v247 offset0:128 offset1:144
	ds_read2_b32 v[244:245], v247 offset0:160 offset1:176
	v_lshlrev_b32_e32 v249, 2, v215
	v_add_u32_e32 v249, 0x21000, v249
	v_add_u32_e32 v248, s89, v215
	v_lshlrev_b32_e32 v237, 2, v248
	v_add_u32_e32 v250, 0x2c00, v237
	ds_read_b128 v[170:173], v249
	ds_read_b128 v[174:177], v249 offset:16
	ds_read_b128 v[178:181], v249 offset:512
	ds_read_b128 v[182:185], v249 offset:528
	ds_read_b128 v[186:189], v249 offset:1024
	ds_read_b128 v[190:193], v249 offset:1040
	ds_read_b128 v[194:197], v249 offset:1536
	ds_read_b128 v[198:201], v249 offset:1552
	v_mul_u32_u24_e32 v151, 0x1600, v246
	v_lshl_add_u32 v151, v248, 1, v151
	v_mov_b32_e32 v219, s64
	v_mov_b32_e32 v220, 0
	v_mov_b32_e32 v221, 0
	v_mov_b32_e32 v222, 0
	v_mov_b32_e32 v223, 0
	v_mov_b32_e32 v224, 0
	v_mov_b32_e32 v225, 0
	v_mov_b32_e32 v226, 0
	v_mov_b32_e32 v227, 0
	v_mov_b32_e32 v228, 0
	v_mov_b32_e32 v229, 0
	v_mov_b32_e32 v230, 0
	v_mov_b32_e32 v231, 0
	v_mov_b32_e32 v232, 0
	v_mov_b32_e32 v233, 0
	v_mov_b32_e32 v234, 0
	v_mov_b32_e32 v235, 0
	s_mul_i32 s56, s75, 0xb000
	s_lshl_b32 s57, s12, 10
	s_add_i32 s56, s56, s57
	v_mul_i32_i24_e32 v150, 0x5800, v216
	v_lshl_add_u32 v150, v215, 2, v150
	v_add_u32_e32 v150, s56, v150
	s_waitcnt lgkmcnt(8)
	v_fmamk_f32 v238, v238, 0x3a800000, v218
	v_fmamk_f32 v239, v239, 0x3a800000, v218
	v_fmamk_f32 v240, v240, 0x3a800000, v218
	v_fmamk_f32 v241, v241, 0x3a800000, v218
	v_fmamk_f32 v242, v242, 0x3a800000, v218
	v_fmamk_f32 v243, v243, 0x3a800000, v218
	v_fmamk_f32 v244, v244, 0x3a800000, v218
	v_fmamk_f32 v245, v245, 0x3a800000, v218
	v_rsq_f32_e32 v238, v238
	v_rsq_f32_e32 v239, v239
	v_rsq_f32_e32 v240, v240
	v_rsq_f32_e32 v241, v241
	v_rsq_f32_e32 v242, v242
	v_rsq_f32_e32 v243, v243
	v_rsq_f32_e32 v244, v244
	v_rsq_f32_e32 v245, v245
	ds_read_b128 v[202:205], v249 offset:2048
	ds_read_b128 v[206:209], v249 offset:2064
	ds_read_b128 v[210:213], v249 offset:2560
	ds_read_b128 v[128:131], v249 offset:2576
	ds_read_b128 v[132:135], v249 offset:3072
	ds_read_b128 v[136:139], v249 offset:3088
	ds_read_b128 v[140:143], v249 offset:3584
	ds_read_b128 v[144:147], v249 offset:3600
	v_pk_mul_f32 v[124:125], v[124:125], v[238:239] op_sel_hi:[1,0]
	v_pk_mul_f32 v[126:127], v[126:127], v[238:239] op_sel_hi:[1,0]
	v_pk_mul_f32 v[92:93], v[92:93], v[238:239] op_sel_hi:[1,0]
	v_pk_mul_f32 v[94:95], v[94:95], v[238:239] op_sel_hi:[1,0]
	v_pk_mul_f32 v[108:109], v[108:109], v[238:239] op_sel_hi:[1,0]
	v_pk_mul_f32 v[110:111], v[110:111], v[238:239] op_sel_hi:[1,0]
	v_pk_mul_f32 v[76:77], v[76:77], v[238:239] op_sel_hi:[1,0]
	v_pk_mul_f32 v[78:79], v[78:79], v[238:239] op_sel_hi:[1,0]
	v_pk_mul_f32 v[120:121], v[120:121], v[238:239] op_sel:[0,1] op_sel_hi:[1,1]
	v_pk_mul_f32 v[122:123], v[122:123], v[238:239] op_sel:[0,1] op_sel_hi:[1,1]
	v_pk_mul_f32 v[88:89], v[88:89], v[238:239] op_sel:[0,1] op_sel_hi:[1,1]
	v_pk_mul_f32 v[90:91], v[90:91], v[238:239] op_sel:[0,1] op_sel_hi:[1,1]
	v_pk_mul_f32 v[104:105], v[104:105], v[238:239] op_sel:[0,1] op_sel_hi:[1,1]
	v_pk_mul_f32 v[106:107], v[106:107], v[238:239] op_sel:[0,1] op_sel_hi:[1,1]
	v_pk_mul_f32 v[72:73], v[72:73], v[238:239] op_sel:[0,1] op_sel_hi:[1,1]
	v_pk_mul_f32 v[74:75], v[74:75], v[238:239] op_sel:[0,1] op_sel_hi:[1,1]
	v_pk_mul_f32 v[116:117], v[116:117], v[240:241] op_sel_hi:[1,0]
	v_pk_mul_f32 v[118:119], v[118:119], v[240:241] op_sel_hi:[1,0]
	v_pk_mul_f32 v[84:85], v[84:85], v[240:241] op_sel_hi:[1,0]
	v_pk_mul_f32 v[86:87], v[86:87], v[240:241] op_sel_hi:[1,0]
	v_pk_mul_f32 v[100:101], v[100:101], v[240:241] op_sel_hi:[1,0]
	v_pk_mul_f32 v[102:103], v[102:103], v[240:241] op_sel_hi:[1,0]
	v_pk_mul_f32 v[68:69], v[68:69], v[240:241] op_sel_hi:[1,0]
	v_pk_mul_f32 v[70:71], v[70:71], v[240:241] op_sel_hi:[1,0]
	v_pk_mul_f32 v[112:113], v[112:113], v[240:241] op_sel:[0,1] op_sel_hi:[1,1]
	v_pk_mul_f32 v[114:115], v[114:115], v[240:241] op_sel:[0,1] op_sel_hi:[1,1]
	v_pk_mul_f32 v[80:81], v[80:81], v[240:241] op_sel:[0,1] op_sel_hi:[1,1]
	v_pk_mul_f32 v[82:83], v[82:83], v[240:241] op_sel:[0,1] op_sel_hi:[1,1]
	v_pk_mul_f32 v[96:97], v[96:97], v[240:241] op_sel:[0,1] op_sel_hi:[1,1]
	v_pk_mul_f32 v[98:99], v[98:99], v[240:241] op_sel:[0,1] op_sel_hi:[1,1]
	v_pk_mul_f32 v[64:65], v[64:65], v[240:241] op_sel:[0,1] op_sel_hi:[1,1]
	v_pk_mul_f32 v[66:67], v[66:67], v[240:241] op_sel:[0,1] op_sel_hi:[1,1]
	v_pk_mul_f32 v[60:61], v[60:61], v[242:243] op_sel_hi:[1,0]
	v_pk_mul_f32 v[62:63], v[62:63], v[242:243] op_sel_hi:[1,0]
	v_pk_mul_f32 v[28:29], v[28:29], v[242:243] op_sel_hi:[1,0]
	v_pk_mul_f32 v[30:31], v[30:31], v[242:243] op_sel_hi:[1,0]
	v_pk_mul_f32 v[44:45], v[44:45], v[242:243] op_sel_hi:[1,0]
	v_pk_mul_f32 v[46:47], v[46:47], v[242:243] op_sel_hi:[1,0]
	v_pk_mul_f32 v[12:13], v[12:13], v[242:243] op_sel_hi:[1,0]
	v_pk_mul_f32 v[14:15], v[14:15], v[242:243] op_sel_hi:[1,0]
	v_pk_mul_f32 v[52:53], v[52:53], v[242:243] op_sel:[0,1] op_sel_hi:[1,1]
	v_pk_mul_f32 v[54:55], v[54:55], v[242:243] op_sel:[0,1] op_sel_hi:[1,1]
	v_pk_mul_f32 v[20:21], v[20:21], v[242:243] op_sel:[0,1] op_sel_hi:[1,1]
	v_pk_mul_f32 v[22:23], v[22:23], v[242:243] op_sel:[0,1] op_sel_hi:[1,1]
	v_pk_mul_f32 v[36:37], v[36:37], v[242:243] op_sel:[0,1] op_sel_hi:[1,1]
	v_pk_mul_f32 v[38:39], v[38:39], v[242:243] op_sel:[0,1] op_sel_hi:[1,1]
	v_pk_mul_f32 v[4:5], v[4:5], v[242:243] op_sel:[0,1] op_sel_hi:[1,1]
	v_pk_mul_f32 v[6:7], v[6:7], v[242:243] op_sel:[0,1] op_sel_hi:[1,1]
	v_pk_mul_f32 v[48:49], v[48:49], v[244:245] op_sel_hi:[1,0]
	v_pk_mul_f32 v[50:51], v[50:51], v[244:245] op_sel_hi:[1,0]
	v_pk_mul_f32 v[16:17], v[16:17], v[244:245] op_sel_hi:[1,0]
	v_pk_mul_f32 v[18:19], v[18:19], v[244:245] op_sel_hi:[1,0]
	v_pk_mul_f32 v[32:33], v[32:33], v[244:245] op_sel_hi:[1,0]
	v_pk_mul_f32 v[34:35], v[34:35], v[244:245] op_sel_hi:[1,0]
	v_pk_mul_f32 v[0:1], v[0:1], v[244:245] op_sel_hi:[1,0]
	v_pk_mul_f32 v[2:3], v[2:3], v[244:245] op_sel_hi:[1,0]
	v_pk_mul_f32 v[56:57], v[56:57], v[244:245] op_sel:[0,1] op_sel_hi:[1,1]
	v_pk_mul_f32 v[58:59], v[58:59], v[244:245] op_sel:[0,1] op_sel_hi:[1,1]
	v_pk_mul_f32 v[24:25], v[24:25], v[244:245] op_sel:[0,1] op_sel_hi:[1,1]
	v_pk_mul_f32 v[26:27], v[26:27], v[244:245] op_sel:[0,1] op_sel_hi:[1,1]
	v_pk_mul_f32 v[40:41], v[40:41], v[244:245] op_sel:[0,1] op_sel_hi:[1,1]
	v_pk_mul_f32 v[42:43], v[42:43], v[244:245] op_sel:[0,1] op_sel_hi:[1,1]
	v_pk_mul_f32 v[8:9], v[8:9], v[244:245] op_sel:[0,1] op_sel_hi:[1,1]
	v_pk_mul_f32 v[10:11], v[10:11], v[244:245] op_sel:[0,1] op_sel_hi:[1,1]
	s_waitcnt lgkmcnt(0)
; __device__ __forceinline__ f32x2 gelu_pk(f32x2 v) {
;     const f32x2 av = __builtin_elementwise_abs(v), d = av * 0.2316418882f + 1.0f;
;     __device__ __forceinline__ void operator()(const f32x4 (&acc)[2][2][4][2], const Unit& u, int wr, int wc, int fr, int fq) const {
;     ...
; #pragma unroll
;                     for (int m = 0; m < 4; ++m) {
;                         f32x4 cv;
;                         if (!samp) {
;                             const f32x4 prev = m ? v[m - 1] : hv;
; #pragma unroll
;                             for (int e = 0; e < 4; ++e) {
;                                 const int vi = __float_as_int(v[m][e]), pi = __float_as_int(prev[e]);
;                                 const int o1 = __builtin_amdgcn_mov_dpp(pi, 0x121, 0xf, 0xf, false);
;                                 const int o2 = __builtin_amdgcn_mov_dpp(pi, 0x122, 0xf, 0xf, false);
;                                 const float p1 = __int_as_float(__builtin_amdgcn_update_dpp(o1, vi, 0x111, 0xf, 0xf, false));
;                                 const float p2 = __int_as_float(__builtin_amdgcn_update_dpp(o2, vi, 0x112, 0xf, 0xf, false));
;                                 cv[e] = cb[e] + cw0[e] * p2 + cw1[e] * p1 + cw2[e] * v[m][e];
;                             }
;                         } else {
;                             const int ns = rowb + 16 * m + fr - MP;
;                             f32x4 s0 = (f32x4){0.f, 0.f, 0.f, 0.f}, s1 = s0;
;                             if (ns < NS) {
;                                 s0 = *(const f32x4*)(state + (size_t)(ns * 2 + 0) * FF2 + oc); s1 = *(const f32x4*)(state + (size_t)(ns * 2 + 1) * FF2 + oc);
;                                 *(f32x4*)(ncs + (size_t)(ns * 2 + 0) * FF2 + oc) = s1; *(f32x4*)(ncs + (size_t)(ns * 2 + 1) * FF2 + oc) = v[m];
;                             }
;                             cv = cb + cw0 * s0 + cw1 * s1 + cw2 * v[m];
;                         }
;                         if (bj == 0) cg[m] = gelu4(cv);
;                         else {
;                             const f32x4 r = cg[m] * cv;
;                             v2u w; w.x = cvt_pk_bf16(r[0], r[1]); w.y = cvt_pk_bf16(r[2], r[3]);
;                             *(v2u*)(ACT + (size_t)(rowb + 16 * m + fr) * FF + 128 * u.pn + 32 * wc + 8 * fq + 4 * n) = w;
;                         }
	v_mbcnt_lo_u32_b32 v218, -1, 0
	v_mbcnt_hi_u32_b32 v218, -1, v218
	v_and_b32_e32 v218, 12, v218
	v_cmp_eq_u32_e32 vcc, 12, v218
	s_nop 1
	v_cndmask_b32_e64 v218, 0, 1.0, vcc
	s_mov_b32 s56, 0x3f07dc22
	v_pk_mul_f32 v[220:221], v[116:117], v[218:219] op_sel_hi:[1,0]
	v_pk_mul_f32 v[222:223], v[118:119], v[218:219] op_sel_hi:[1,0]
	v_pk_fma_f32 v[254:255], v[202:203], v[112:113], v[132:133]
	v_pk_fma_f32 v[148:149], v[204:205], v[114:115], v[134:135]
	v_fmac_f32_dpp v254, v112, v186 row_shr:1 row_mask:0xf bank_mask:0xf
	v_fmac_f32_dpp v255, v113, v187 row_shr:1 row_mask:0xf bank_mask:0xf
	v_fmac_f32_dpp v148, v114, v188 row_shr:1 row_mask:0xf bank_mask:0xf
	v_fmac_f32_dpp v149, v115, v189 row_shr:1 row_mask:0xf bank_mask:0xf
	v_fmac_f32_dpp v254, v112, v170 row_shr:2 row_mask:0xf bank_mask:0xf
	v_fmac_f32_dpp v255, v113, v171 row_shr:2 row_mask:0xf bank_mask:0xf
	v_fmac_f32_dpp v148, v114, v172 row_shr:2 row_mask:0xf bank_mask:0xf
	v_fmac_f32_dpp v149, v115, v173 row_shr:2 row_mask:0xf bank_mask:0xf
	v_fmac_f32_dpp v254, v220, v186 row_ror:1 row_mask:0xf bank_mask:0x1
	v_fmac_f32_dpp v255, v221, v187 row_ror:1 row_mask:0xf bank_mask:0x1
	v_fmac_f32_dpp v148, v222, v188 row_ror:1 row_mask:0xf bank_mask:0x1
	v_fmac_f32_dpp v149, v223, v189 row_ror:1 row_mask:0xf bank_mask:0x1
	v_fmac_f32_dpp v254, v220, v170 row_ror:2 row_mask:0xf bank_mask:0x1
	v_fmac_f32_dpp v255, v221, v171 row_ror:2 row_mask:0xf bank_mask:0x1
	v_fmac_f32_dpp v148, v222, v172 row_ror:2 row_mask:0xf bank_mask:0x1
	v_fmac_f32_dpp v149, v223, v173 row_ror:2 row_mask:0xf bank_mask:0x1
	v_fma_f32 v246, |v254|, s38, 1.0
	v_fma_f32 v247, |v255|, s38, 1.0
	v_fma_f32 v248, |v148|, s38, 1.0
	v_fma_f32 v249, |v149|, s38, 1.0
	v_pk_mul_f32 v[250:251], v[254:255], v[254:255]
	v_pk_mul_f32 v[252:253], v[148:149], v[148:149]
	v_rcp_f32_e32 v246, v246
	v_rcp_f32_e32 v247, v247
	v_rcp_f32_e32 v248, v248
	v_rcp_f32_e32 v249, v249
	v_pk_mul_f32 v[250:251], v[250:251], s[72:73] op_sel_hi:[1,0]
	v_pk_mul_f32 v[252:253], v[252:253], s[72:73] op_sel_hi:[1,0]
	v_exp_f32_e32 v250, v250
	v_exp_f32_e32 v251, v251
	v_exp_f32_e32 v252, v252
	v_exp_f32_e32 v253, v253
	v_pk_fma_f32 v[238:239], v[246:247], s[56:57], v[218:219] op_sel:[0,0,1] op_sel_hi:[1,0,1]
	v_pk_fma_f32 v[240:241], v[248:249], s[56:57], v[218:219] op_sel:[0,0,1] op_sel_hi:[1,0,1]
	v_pk_fma_f32 v[238:239], v[246:247], v[238:239], s[66:67] op_sel_hi:[1,1,0]
	v_pk_fma_f32 v[240:241], v[248:249], v[240:241], s[66:67] op_sel_hi:[1,1,0]
	v_pk_fma_f32 v[238:239], v[246:247], v[238:239], s[68:69] op_sel_hi:[1,1,0]
	v_pk_fma_f32 v[240:241], v[248:249], v[240:241], s[68:69] op_sel_hi:[1,1,0]
	v_pk_fma_f32 v[238:239], v[246:247], v[238:239], s[70:71] op_sel_hi:[1,1,0]
	v_pk_fma_f32 v[240:241], v[248:249], v[240:241], s[70:71] op_sel_hi:[1,1,0]
	v_pk_mul_f32 v[238:239], v[246:247], v[238:239]
	v_pk_mul_f32 v[240:241], v[248:249], v[240:241]
	v_pk_mul_f32 v[238:239], v[250:251], v[238:239]
	v_pk_mul_f32 v[240:241], v[252:253], v[240:241]
	v_max_f32_e32 v246, 0, v254
	v_max_f32_e32 v247, 0, v255
	v_max_f32_e32 v248, 0, v148
	v_max_f32_e32 v249, 0, v149
	v_fma_f32 v238, -|v254|, v238, v246
	v_fma_f32 v239, -|v255|, v239, v247
	v_fma_f32 v240, -|v148|, v240, v248
	v_fma_f32 v241, -|v149|, v241, v249
	v_pk_mul_f32 v[220:221], v[100:101], v[218:219] op_sel_hi:[1,0]
	v_pk_mul_f32 v[222:223], v[102:103], v[218:219] op_sel_hi:[1,0]
	v_pk_fma_f32 v[254:255], v[210:211], v[96:97], v[140:141]
	v_pk_fma_f32 v[148:149], v[212:213], v[98:99], v[142:143]
	v_fmac_f32_dpp v254, v96, v194 row_shr:1 row_mask:0xf bank_mask:0xf
	v_fmac_f32_dpp v255, v97, v195 row_shr:1 row_mask:0xf bank_mask:0xf
	v_fmac_f32_dpp v148, v98, v196 row_shr:1 row_mask:0xf bank_mask:0xf
	v_fmac_f32_dpp v149, v99, v197 row_shr:1 row_mask:0xf bank_mask:0xf
	v_fmac_f32_dpp v254, v96, v178 row_shr:2 row_mask:0xf bank_mask:0xf
	v_fmac_f32_dpp v255, v97, v179 row_shr:2 row_mask:0xf bank_mask:0xf
	v_fmac_f32_dpp v148, v98, v180 row_shr:2 row_mask:0xf bank_mask:0xf
	v_fmac_f32_dpp v149, v99, v181 row_shr:2 row_mask:0xf bank_mask:0xf
	v_fmac_f32_dpp v254, v220, v194 row_ror:1 row_mask:0xf bank_mask:0x1
	v_fmac_f32_dpp v255, v221, v195 row_ror:1 row_mask:0xf bank_mask:0x1
	v_fmac_f32_dpp v148, v222, v196 row_ror:1 row_mask:0xf bank_mask:0x1
	v_fmac_f32_dpp v149, v223, v197 row_ror:1 row_mask:0xf bank_mask:0x1
	v_fmac_f32_dpp v254, v220, v178 row_ror:2 row_mask:0xf bank_mask:0x1
	v_fmac_f32_dpp v255, v221, v179 row_ror:2 row_mask:0xf bank_mask:0x1
	v_fmac_f32_dpp v148, v222, v180 row_ror:2 row_mask:0xf bank_mask:0x1
	v_fmac_f32_dpp v149, v223, v181 row_ror:2 row_mask:0xf bank_mask:0x1
	v_pk_mul_f32 v[254:255], v[238:239], v[254:255]
	v_pk_mul_f32 v[148:149], v[240:241], v[148:149]
	v_cvt_pk_bf16_f32 v242, v254, v255
	v_cvt_pk_bf16_f32 v243, v148, v149
	v_pk_mul_f32 v[220:221], v[84:85], v[218:219] op_sel_hi:[1,0]
	v_pk_mul_f32 v[222:223], v[86:87], v[218:219] op_sel_hi:[1,0]
	v_pk_fma_f32 v[254:255], v[206:207], v[80:81], v[136:137]
	v_pk_fma_f32 v[148:149], v[208:209], v[82:83], v[138:139]
	v_fmac_f32_dpp v254, v80, v190 row_shr:1 row_mask:0xf bank_mask:0xf
	v_fmac_f32_dpp v255, v81, v191 row_shr:1 row_mask:0xf bank_mask:0xf
	v_fmac_f32_dpp v148, v82, v192 row_shr:1 row_mask:0xf bank_mask:0xf
	v_fmac_f32_dpp v149, v83, v193 row_shr:1 row_mask:0xf bank_mask:0xf
	v_fmac_f32_dpp v254, v80, v174 row_shr:2 row_mask:0xf bank_mask:0xf
	v_fmac_f32_dpp v255, v81, v175 row_shr:2 row_mask:0xf bank_mask:0xf
	v_fmac_f32_dpp v148, v82, v176 row_shr:2 row_mask:0xf bank_mask:0xf
	v_fmac_f32_dpp v149, v83, v177 row_shr:2 row_mask:0xf bank_mask:0xf
	v_fmac_f32_dpp v254, v220, v190 row_ror:1 row_mask:0xf bank_mask:0x1
; __device__ __forceinline__ f32x2 gelu_pk(f32x2 v) {
;     const f32x2 av = __builtin_elementwise_abs(v), d = av * 0.2316418882f + 1.0f;
;     __device__ __forceinline__ void operator()(const f32x4 (&acc)[2][2][4][2], const Unit& u, int wr, int wc, int fr, int fq) const {
;     ...
; #pragma unroll
;                     for (int m = 0; m < 4; ++m) {
;                         f32x4 cv;
;                         if (!samp) {
;                             const f32x4 prev = m ? v[m - 1] : hv;
; #pragma unroll
;                             for (int e = 0; e < 4; ++e) {
;                                 const int vi = __float_as_int(v[m][e]), pi = __float_as_int(prev[e]);
;                                 const int o1 = __builtin_amdgcn_mov_dpp(pi, 0x121, 0xf, 0xf, false);
;                                 const int o2 = __builtin_amdgcn_mov_dpp(pi, 0x122, 0xf, 0xf, false);
;                                 const float p1 = __int_as_float(__builtin_amdgcn_update_dpp(o1, vi, 0x111, 0xf, 0xf, false));
;                                 const float p2 = __int_as_float(__builtin_amdgcn_update_dpp(o2, vi, 0x112, 0xf, 0xf, false));
;                                 cv[e] = cb[e] + cw0[e] * p2 + cw1[e] * p1 + cw2[e] * v[m][e];
;                             }
;                         } else {
;                             const int ns = rowb + 16 * m + fr - MP;
;                             f32x4 s0 = (f32x4){0.f, 0.f, 0.f, 0.f}, s1 = s0;
;                             if (ns < NS) {
;                                 s0 = *(const f32x4*)(state + (size_t)(ns * 2 + 0) * FF2 + oc); s1 = *(const f32x4*)(state + (size_t)(ns * 2 + 1) * FF2 + oc);
;                                 *(f32x4*)(ncs + (size_t)(ns * 2 + 0) * FF2 + oc) = s1; *(f32x4*)(ncs + (size_t)(ns * 2 + 1) * FF2 + oc) = v[m];
;                             }
;                             cv = cb + cw0 * s0 + cw1 * s1 + cw2 * v[m];
;                         }
;                         if (bj == 0) cg[m] = gelu4(cv);
;                         else {
;                             const f32x4 r = cg[m] * cv;
;                             v2u w; w.x = cvt_pk_bf16(r[0], r[1]); w.y = cvt_pk_bf16(r[2], r[3]);
;                             *(v2u*)(ACT + (size_t)(rowb + 16 * m + fr) * FF + 128 * u.pn + 32 * wc + 8 * fq + 4 * n) = w;
;                         }
	v_fmac_f32_dpp v255, v221, v191 row_ror:1 row_mask:0xf bank_mask:0x1
	v_fmac_f32_dpp v148, v222, v192 row_ror:1 row_mask:0xf bank_mask:0x1
	v_fmac_f32_dpp v149, v223, v193 row_ror:1 row_mask:0xf bank_mask:0x1
	v_fmac_f32_dpp v254, v220, v174 row_ror:2 row_mask:0xf bank_mask:0x1
	v_fmac_f32_dpp v255, v221, v175 row_ror:2 row_mask:0xf bank_mask:0x1
	v_fmac_f32_dpp v148, v222, v176 row_ror:2 row_mask:0xf bank_mask:0x1
	v_fmac_f32_dpp v149, v223, v177 row_ror:2 row_mask:0xf bank_mask:0x1
	v_fma_f32 v246, |v254|, s38, 1.0
	v_fma_f32 v247, |v255|, s38, 1.0
	v_fma_f32 v248, |v148|, s38, 1.0
	v_fma_f32 v249, |v149|, s38, 1.0
	v_pk_mul_f32 v[250:251], v[254:255], v[254:255]
	v_pk_mul_f32 v[252:253], v[148:149], v[148:149]
	v_rcp_f32_e32 v246, v246
	v_rcp_f32_e32 v247, v247
	v_rcp_f32_e32 v248, v248
	v_rcp_f32_e32 v249, v249
	v_pk_mul_f32 v[250:251], v[250:251], s[72:73] op_sel_hi:[1,0]
	v_pk_mul_f32 v[252:253], v[252:253], s[72:73] op_sel_hi:[1,0]
	v_exp_f32_e32 v250, v250
	v_exp_f32_e32 v251, v251
	v_exp_f32_e32 v252, v252
	v_exp_f32_e32 v253, v253
	v_pk_fma_f32 v[238:239], v[246:247], s[56:57], v[218:219] op_sel:[0,0,1] op_sel_hi:[1,0,1]
	v_pk_fma_f32 v[240:241], v[248:249], s[56:57], v[218:219] op_sel:[0,0,1] op_sel_hi:[1,0,1]
	v_pk_fma_f32 v[238:239], v[246:247], v[238:239], s[66:67] op_sel_hi:[1,1,0]
	v_pk_fma_f32 v[240:241], v[248:249], v[240:241], s[66:67] op_sel_hi:[1,1,0]
	v_pk_fma_f32 v[238:239], v[246:247], v[238:239], s[68:69] op_sel_hi:[1,1,0]
	v_pk_fma_f32 v[240:241], v[248:249], v[240:241], s[68:69] op_sel_hi:[1,1,0]
	v_pk_fma_f32 v[238:239], v[246:247], v[238:239], s[70:71] op_sel_hi:[1,1,0]
	v_pk_fma_f32 v[240:241], v[248:249], v[240:241], s[70:71] op_sel_hi:[1,1,0]
	v_pk_mul_f32 v[238:239], v[246:247], v[238:239]
	v_pk_mul_f32 v[240:241], v[248:249], v[240:241]
	v_pk_mul_f32 v[238:239], v[250:251], v[238:239]
	v_pk_mul_f32 v[240:241], v[252:253], v[240:241]
	v_max_f32_e32 v246, 0, v254
	v_max_f32_e32 v247, 0, v255
	v_max_f32_e32 v248, 0, v148
	v_max_f32_e32 v249, 0, v149
	v_fma_f32 v238, -|v254|, v238, v246
	v_fma_f32 v239, -|v255|, v239, v247
	v_fma_f32 v240, -|v148|, v240, v248
	v_fma_f32 v241, -|v149|, v241, v249
	v_pk_mul_f32 v[220:221], v[68:69], v[218:219] op_sel_hi:[1,0]
	v_pk_mul_f32 v[222:223], v[70:71], v[218:219] op_sel_hi:[1,0]
	v_pk_fma_f32 v[254:255], v[128:129], v[64:65], v[144:145]
	v_pk_fma_f32 v[148:149], v[130:131], v[66:67], v[146:147]
	v_fmac_f32_dpp v254, v64, v198 row_shr:1 row_mask:0xf bank_mask:0xf
	v_fmac_f32_dpp v255, v65, v199 row_shr:1 row_mask:0xf bank_mask:0xf
	v_fmac_f32_dpp v148, v66, v200 row_shr:1 row_mask:0xf bank_mask:0xf
	v_fmac_f32_dpp v149, v67, v201 row_shr:1 row_mask:0xf bank_mask:0xf
	v_fmac_f32_dpp v254, v64, v182 row_shr:2 row_mask:0xf bank_mask:0xf
	v_fmac_f32_dpp v255, v65, v183 row_shr:2 row_mask:0xf bank_mask:0xf
	v_fmac_f32_dpp v148, v66, v184 row_shr:2 row_mask:0xf bank_mask:0xf
	v_fmac_f32_dpp v149, v67, v185 row_shr:2 row_mask:0xf bank_mask:0xf
	v_fmac_f32_dpp v254, v220, v198 row_ror:1 row_mask:0xf bank_mask:0x1
	v_fmac_f32_dpp v255, v221, v199 row_ror:1 row_mask:0xf bank_mask:0x1
	v_fmac_f32_dpp v148, v222, v200 row_ror:1 row_mask:0xf bank_mask:0x1
	v_fmac_f32_dpp v149, v223, v201 row_ror:1 row_mask:0xf bank_mask:0x1
	v_fmac_f32_dpp v254, v220, v182 row_ror:2 row_mask:0xf bank_mask:0x1
	v_fmac_f32_dpp v255, v221, v183 row_ror:2 row_mask:0xf bank_mask:0x1
	v_fmac_f32_dpp v148, v222, v184 row_ror:2 row_mask:0xf bank_mask:0x1
	v_fmac_f32_dpp v149, v223, v185 row_ror:2 row_mask:0xf bank_mask:0x1
	v_pk_mul_f32 v[254:255], v[238:239], v[254:255]
	v_pk_mul_f32 v[148:149], v[240:241], v[148:149]
	v_cvt_pk_bf16_f32 v244, v254, v255
	v_cvt_pk_bf16_f32 v245, v148, v149
	s_add_u32 s56, s46, 0x42000
	s_addc_u32 s57, s47, 0
	global_store_dwordx4 v151, v[242:245], s[56:57]
	s_mov_b32 s56, 0x3f07dc22
	v_pk_mul_f32 v[112:113], v[120:121], v[218:219] op_sel_hi:[1,0]
	v_pk_mul_f32 v[114:115], v[122:123], v[218:219] op_sel_hi:[1,0]
	v_pk_fma_f32 v[254:255], v[202:203], v[116:117], v[132:133]
	v_pk_fma_f32 v[148:149], v[204:205], v[118:119], v[134:135]
	v_fmac_f32_dpp v254, v116, v186 row_shr:1 row_mask:0xf bank_mask:0xf
	v_fmac_f32_dpp v255, v117, v187 row_shr:1 row_mask:0xf bank_mask:0xf
	v_fmac_f32_dpp v148, v118, v188 row_shr:1 row_mask:0xf bank_mask:0xf
	v_fmac_f32_dpp v149, v119, v189 row_shr:1 row_mask:0xf bank_mask:0xf
	v_fmac_f32_dpp v254, v116, v170 row_shr:2 row_mask:0xf bank_mask:0xf
	v_fmac_f32_dpp v255, v117, v171 row_shr:2 row_mask:0xf bank_mask:0xf
	v_fmac_f32_dpp v148, v118, v172 row_shr:2 row_mask:0xf bank_mask:0xf
	v_fmac_f32_dpp v149, v119, v173 row_shr:2 row_mask:0xf bank_mask:0xf
	v_fmac_f32_dpp v254, v112, v186 row_ror:1 row_mask:0xf bank_mask:0x1
	v_fmac_f32_dpp v255, v113, v187 row_ror:1 row_mask:0xf bank_mask:0x1
	v_fmac_f32_dpp v148, v114, v188 row_ror:1 row_mask:0xf bank_mask:0x1
	v_fmac_f32_dpp v149, v115, v189 row_ror:1 row_mask:0xf bank_mask:0x1
	v_fmac_f32_dpp v254, v112, v170 row_ror:2 row_mask:0xf bank_mask:0x1
	v_fmac_f32_dpp v255, v113, v171 row_ror:2 row_mask:0xf bank_mask:0x1
	v_fmac_f32_dpp v148, v114, v172 row_ror:2 row_mask:0xf bank_mask:0x1
	v_fmac_f32_dpp v149, v115, v173 row_ror:2 row_mask:0xf bank_mask:0x1
	v_fma_f32 v246, |v254|, s38, 1.0
	v_fma_f32 v247, |v255|, s38, 1.0
	v_fma_f32 v248, |v148|, s38, 1.0
	v_fma_f32 v249, |v149|, s38, 1.0
	v_pk_mul_f32 v[250:251], v[254:255], v[254:255]
	v_pk_mul_f32 v[252:253], v[148:149], v[148:149]
	v_rcp_f32_e32 v246, v246
	v_rcp_f32_e32 v247, v247
	v_rcp_f32_e32 v248, v248
	v_rcp_f32_e32 v249, v249
	v_pk_mul_f32 v[250:251], v[250:251], s[72:73] op_sel_hi:[1,0]
	v_pk_mul_f32 v[252:253], v[252:253], s[72:73] op_sel_hi:[1,0]
; __device__ __forceinline__ f32x2 gelu_pk(f32x2 v) {
;     const f32x2 av = __builtin_elementwise_abs(v), d = av * 0.2316418882f + 1.0f;
;     __device__ __forceinline__ void operator()(const f32x4 (&acc)[2][2][4][2], const Unit& u, int wr, int wc, int fr, int fq) const {
;     ...
; #pragma unroll
;                     for (int m = 0; m < 4; ++m) {
;                         f32x4 cv;
;                         if (!samp) {
;                             const f32x4 prev = m ? v[m - 1] : hv;
; #pragma unroll
;                             for (int e = 0; e < 4; ++e) {
;                                 const int vi = __float_as_int(v[m][e]), pi = __float_as_int(prev[e]);
;                                 const int o1 = __builtin_amdgcn_mov_dpp(pi, 0x121, 0xf, 0xf, false);
;                                 const int o2 = __builtin_amdgcn_mov_dpp(pi, 0x122, 0xf, 0xf, false);
;                                 const float p1 = __int_as_float(__builtin_amdgcn_update_dpp(o1, vi, 0x111, 0xf, 0xf, false));
;                                 const float p2 = __int_as_float(__builtin_amdgcn_update_dpp(o2, vi, 0x112, 0xf, 0xf, false));
;                                 cv[e] = cb[e] + cw0[e] * p2 + cw1[e] * p1 + cw2[e] * v[m][e];
;                             }
;                         } else {
;                             const int ns = rowb + 16 * m + fr - MP;
;                             f32x4 s0 = (f32x4){0.f, 0.f, 0.f, 0.f}, s1 = s0;
;                             if (ns < NS) {
;                                 s0 = *(const f32x4*)(state + (size_t)(ns * 2 + 0) * FF2 + oc); s1 = *(const f32x4*)(state + (size_t)(ns * 2 + 1) * FF2 + oc);
;                                 *(f32x4*)(ncs + (size_t)(ns * 2 + 0) * FF2 + oc) = s1; *(f32x4*)(ncs + (size_t)(ns * 2 + 1) * FF2 + oc) = v[m];
;                             }
;                             cv = cb + cw0 * s0 + cw1 * s1 + cw2 * v[m];
;                         }
;                         if (bj == 0) cg[m] = gelu4(cv);
;                         else {
;                             const f32x4 r = cg[m] * cv;
;                             v2u w; w.x = cvt_pk_bf16(r[0], r[1]); w.y = cvt_pk_bf16(r[2], r[3]);
;                             *(v2u*)(ACT + (size_t)(rowb + 16 * m + fr) * FF + 128 * u.pn + 32 * wc + 8 * fq + 4 * n) = w;
;                         }
	v_exp_f32_e32 v250, v250
	v_exp_f32_e32 v251, v251
	v_exp_f32_e32 v252, v252
	v_exp_f32_e32 v253, v253
	v_pk_fma_f32 v[238:239], v[246:247], s[56:57], v[218:219] op_sel:[0,0,1] op_sel_hi:[1,0,1]
	v_pk_fma_f32 v[240:241], v[248:249], s[56:57], v[218:219] op_sel:[0,0,1] op_sel_hi:[1,0,1]
	v_pk_fma_f32 v[238:239], v[246:247], v[238:239], s[66:67] op_sel_hi:[1,1,0]
	v_pk_fma_f32 v[240:241], v[248:249], v[240:241], s[66:67] op_sel_hi:[1,1,0]
	v_pk_fma_f32 v[238:239], v[246:247], v[238:239], s[68:69] op_sel_hi:[1,1,0]
	v_pk_fma_f32 v[240:241], v[248:249], v[240:241], s[68:69] op_sel_hi:[1,1,0]
	v_pk_fma_f32 v[238:239], v[246:247], v[238:239], s[70:71] op_sel_hi:[1,1,0]
	v_pk_fma_f32 v[240:241], v[248:249], v[240:241], s[70:71] op_sel_hi:[1,1,0]
	v_pk_mul_f32 v[238:239], v[246:247], v[238:239]
	v_pk_mul_f32 v[240:241], v[248:249], v[240:241]
	v_pk_mul_f32 v[238:239], v[250:251], v[238:239]
	v_pk_mul_f32 v[240:241], v[252:253], v[240:241]
	v_max_f32_e32 v246, 0, v254
	v_max_f32_e32 v247, 0, v255
	v_max_f32_e32 v248, 0, v148
	v_max_f32_e32 v249, 0, v149
	v_fma_f32 v238, -|v254|, v238, v246
	v_fma_f32 v239, -|v255|, v239, v247
	v_fma_f32 v240, -|v148|, v240, v248
	v_fma_f32 v241, -|v149|, v241, v249
	v_pk_mul_f32 v[112:113], v[104:105], v[218:219] op_sel_hi:[1,0]
	v_pk_mul_f32 v[114:115], v[106:107], v[218:219] op_sel_hi:[1,0]
	v_pk_fma_f32 v[254:255], v[210:211], v[100:101], v[140:141]
	v_pk_fma_f32 v[148:149], v[212:213], v[102:103], v[142:143]
	v_fmac_f32_dpp v254, v100, v194 row_shr:1 row_mask:0xf bank_mask:0xf
	v_fmac_f32_dpp v255, v101, v195 row_shr:1 row_mask:0xf bank_mask:0xf
	v_fmac_f32_dpp v148, v102, v196 row_shr:1 row_mask:0xf bank_mask:0xf
	v_fmac_f32_dpp v149, v103, v197 row_shr:1 row_mask:0xf bank_mask:0xf
	v_fmac_f32_dpp v254, v100, v178 row_shr:2 row_mask:0xf bank_mask:0xf
	v_fmac_f32_dpp v255, v101, v179 row_shr:2 row_mask:0xf bank_mask:0xf
	v_fmac_f32_dpp v148, v102, v180 row_shr:2 row_mask:0xf bank_mask:0xf
	v_fmac_f32_dpp v149, v103, v181 row_shr:2 row_mask:0xf bank_mask:0xf
	v_fmac_f32_dpp v254, v112, v194 row_ror:1 row_mask:0xf bank_mask:0x1
	v_fmac_f32_dpp v255, v113, v195 row_ror:1 row_mask:0xf bank_mask:0x1
	v_fmac_f32_dpp v148, v114, v196 row_ror:1 row_mask:0xf bank_mask:0x1
	v_fmac_f32_dpp v149, v115, v197 row_ror:1 row_mask:0xf bank_mask:0x1
	v_fmac_f32_dpp v254, v112, v178 row_ror:2 row_mask:0xf bank_mask:0x1
	v_fmac_f32_dpp v255, v113, v179 row_ror:2 row_mask:0xf bank_mask:0x1
	v_fmac_f32_dpp v148, v114, v180 row_ror:2 row_mask:0xf bank_mask:0x1
	v_fmac_f32_dpp v149, v115, v181 row_ror:2 row_mask:0xf bank_mask:0x1
	v_pk_mul_f32 v[254:255], v[238:239], v[254:255]
	v_pk_mul_f32 v[148:149], v[240:241], v[148:149]
	v_cvt_pk_bf16_f32 v242, v254, v255
	v_cvt_pk_bf16_f32 v243, v148, v149
	v_pk_mul_f32 v[112:113], v[88:89], v[218:219] op_sel_hi:[1,0]
	v_pk_mul_f32 v[114:115], v[90:91], v[218:219] op_sel_hi:[1,0]
	v_pk_fma_f32 v[254:255], v[206:207], v[84:85], v[136:137]
	v_pk_fma_f32 v[148:149], v[208:209], v[86:87], v[138:139]
	v_fmac_f32_dpp v254, v84, v190 row_shr:1 row_mask:0xf bank_mask:0xf
	v_fmac_f32_dpp v255, v85, v191 row_shr:1 row_mask:0xf bank_mask:0xf
	v_fmac_f32_dpp v148, v86, v192 row_shr:1 row_mask:0xf bank_mask:0xf
	v_fmac_f32_dpp v149, v87, v193 row_shr:1 row_mask:0xf bank_mask:0xf
	v_fmac_f32_dpp v254, v84, v174 row_shr:2 row_mask:0xf bank_mask:0xf
	v_fmac_f32_dpp v255, v85, v175 row_shr:2 row_mask:0xf bank_mask:0xf
	v_fmac_f32_dpp v148, v86, v176 row_shr:2 row_mask:0xf bank_mask:0xf
	v_fmac_f32_dpp v149, v87, v177 row_shr:2 row_mask:0xf bank_mask:0xf
	v_fmac_f32_dpp v254, v112, v190 row_ror:1 row_mask:0xf bank_mask:0x1
	v_fmac_f32_dpp v255, v113, v191 row_ror:1 row_mask:0xf bank_mask:0x1
	v_fmac_f32_dpp v148, v114, v192 row_ror:1 row_mask:0xf bank_mask:0x1
	v_fmac_f32_dpp v149, v115, v193 row_ror:1 row_mask:0xf bank_mask:0x1
	v_fmac_f32_dpp v254, v112, v174 row_ror:2 row_mask:0xf bank_mask:0x1
	v_fmac_f32_dpp v255, v113, v175 row_ror:2 row_mask:0xf bank_mask:0x1
	v_fmac_f32_dpp v148, v114, v176 row_ror:2 row_mask:0xf bank_mask:0x1
	v_fmac_f32_dpp v149, v115, v177 row_ror:2 row_mask:0xf bank_mask:0x1
	v_fma_f32 v246, |v254|, s38, 1.0
	v_fma_f32 v247, |v255|, s38, 1.0
	v_fma_f32 v248, |v148|, s38, 1.0
	v_fma_f32 v249, |v149|, s38, 1.0
	v_pk_mul_f32 v[250:251], v[254:255], v[254:255]
	v_pk_mul_f32 v[252:253], v[148:149], v[148:149]
;     __device__ __forceinline__ void operator()(const f32x4 (&acc)[2][2][4][2], const Unit& u, int wr, int wc, int fr, int fq) const {
;     ...
;                     if (!samp) {
;                         if ((blk & 31) != 0 && fr >= 14) hv = *(const f32x4*)(HALO + (size_t)(2 * blk + fr - 14) * FF2 + cgc);
;                         if ((u.pm & 7) == 7 && ai == 1 && wr == 1 && fr >= 14) *(f32x4*)(ncp + (size_t)((u.pm >> 3) * 2 + (fr - 14)) * FF2 + oc) = v[3];
;                     }
; #pragma unroll
;                     for (int m = 0; m < 4; ++m) {
;                         f32x4 cv;
;                         if (!samp) {
;                             const f32x4 prev = m ? v[m - 1] : hv;
; #pragma unroll
;                             for (int e = 0; e < 4; ++e) {
;                                 const int vi = __float_as_int(v[m][e]), pi = __float_as_int(prev[e]);
;                                 const int o1 = __builtin_amdgcn_mov_dpp(pi, 0x121, 0xf, 0xf, false);
;                                 const int o2 = __builtin_amdgcn_mov_dpp(pi, 0x122, 0xf, 0xf, false);
;                                 const float p1 = __int_as_float(__builtin_amdgcn_update_dpp(o1, vi, 0x111, 0xf, 0xf, false));
;                                 const float p2 = __int_as_float(__builtin_amdgcn_update_dpp(o2, vi, 0x112, 0xf, 0xf, false));
;                                 cv[e] = cb[e] + cw0[e] * p2 + cw1[e] * p1 + cw2[e] * v[m][e];
;                             }
;                         } else {
;                             const int ns = rowb + 16 * m + fr - MP;
;                             f32x4 s0 = (f32x4){0.f, 0.f, 0.f, 0.f}, s1 = s0;
;                             if (ns < NS) {
;                                 s0 = *(const f32x4*)(state + (size_t)(ns * 2 + 0) * FF2 + oc); s1 = *(const f32x4*)(state + (size_t)(ns * 2 + 1) * FF2 + oc);
;                                 *(f32x4*)(ncs + (size_t)(ns * 2 + 0) * FF2 + oc) = s1; *(f32x4*)(ncs + (size_t)(ns * 2 + 1) * FF2 + oc) = v[m];
;                             }
;                             cv = cb + cw0 * s0 + cw1 * s1 + cw2 * v[m];
;                         }
;                         if (bj == 0) cg[m] = gelu4(cv);
;                         else {
;                             const f32x4 r = cg[m] * cv;
;                             v2u w; w.x = cvt_pk_bf16(r[0], r[1]); w.y = cvt_pk_bf16(r[2], r[3]);
	v_rcp_f32_e32 v246, v246
	v_rcp_f32_e32 v247, v247
	v_rcp_f32_e32 v248, v248
	v_rcp_f32_e32 v249, v249
	v_pk_mul_f32 v[250:251], v[250:251], s[72:73] op_sel_hi:[1,0]
	v_pk_mul_f32 v[252:253], v[252:253], s[72:73] op_sel_hi:[1,0]
	v_exp_f32_e32 v250, v250
	v_exp_f32_e32 v251, v251
	v_exp_f32_e32 v252, v252
	v_exp_f32_e32 v253, v253
	v_pk_fma_f32 v[238:239], v[246:247], s[56:57], v[218:219] op_sel:[0,0,1] op_sel_hi:[1,0,1]
	v_pk_fma_f32 v[240:241], v[248:249], s[56:57], v[218:219] op_sel:[0,0,1] op_sel_hi:[1,0,1]
	v_pk_fma_f32 v[238:239], v[246:247], v[238:239], s[66:67] op_sel_hi:[1,1,0]
	v_pk_fma_f32 v[240:241], v[248:249], v[240:241], s[66:67] op_sel_hi:[1,1,0]
	v_pk_fma_f32 v[238:239], v[246:247], v[238:239], s[68:69] op_sel_hi:[1,1,0]
	v_pk_fma_f32 v[240:241], v[248:249], v[240:241], s[68:69] op_sel_hi:[1,1,0]
	v_pk_fma_f32 v[238:239], v[246:247], v[238:239], s[70:71] op_sel_hi:[1,1,0]
	v_pk_fma_f32 v[240:241], v[248:249], v[240:241], s[70:71] op_sel_hi:[1,1,0]
	v_pk_mul_f32 v[238:239], v[246:247], v[238:239]
	v_pk_mul_f32 v[240:241], v[248:249], v[240:241]
	v_pk_mul_f32 v[238:239], v[250:251], v[238:239]
	v_pk_mul_f32 v[240:241], v[252:253], v[240:241]
	v_max_f32_e32 v246, 0, v254
	v_max_f32_e32 v247, 0, v255
	v_max_f32_e32 v248, 0, v148
	v_max_f32_e32 v249, 0, v149
	v_fma_f32 v238, -|v254|, v238, v246
	v_fma_f32 v239, -|v255|, v239, v247
	v_fma_f32 v240, -|v148|, v240, v248
	v_fma_f32 v241, -|v149|, v241, v249
	v_pk_mul_f32 v[112:113], v[72:73], v[218:219] op_sel_hi:[1,0]
	v_pk_mul_f32 v[114:115], v[74:75], v[218:219] op_sel_hi:[1,0]
	v_pk_fma_f32 v[254:255], v[128:129], v[68:69], v[144:145]
	v_pk_fma_f32 v[148:149], v[130:131], v[70:71], v[146:147]
	v_fmac_f32_dpp v254, v68, v198 row_shr:1 row_mask:0xf bank_mask:0xf
	v_fmac_f32_dpp v255, v69, v199 row_shr:1 row_mask:0xf bank_mask:0xf
	v_fmac_f32_dpp v148, v70, v200 row_shr:1 row_mask:0xf bank_mask:0xf
	v_fmac_f32_dpp v149, v71, v201 row_shr:1 row_mask:0xf bank_mask:0xf
	v_fmac_f32_dpp v254, v68, v182 row_shr:2 row_mask:0xf bank_mask:0xf
	v_fmac_f32_dpp v255, v69, v183 row_shr:2 row_mask:0xf bank_mask:0xf
	v_fmac_f32_dpp v148, v70, v184 row_shr:2 row_mask:0xf bank_mask:0xf
	v_fmac_f32_dpp v149, v71, v185 row_shr:2 row_mask:0xf bank_mask:0xf
	v_fmac_f32_dpp v254, v112, v198 row_ror:1 row_mask:0xf bank_mask:0x1
	v_fmac_f32_dpp v255, v113, v199 row_ror:1 row_mask:0xf bank_mask:0x1
	v_fmac_f32_dpp v148, v114, v200 row_ror:1 row_mask:0xf bank_mask:0x1
	v_fmac_f32_dpp v149, v115, v201 row_ror:1 row_mask:0xf bank_mask:0x1
	v_fmac_f32_dpp v254, v112, v182 row_ror:2 row_mask:0xf bank_mask:0x1
	v_fmac_f32_dpp v255, v113, v183 row_ror:2 row_mask:0xf bank_mask:0x1
	v_fmac_f32_dpp v148, v114, v184 row_ror:2 row_mask:0xf bank_mask:0x1
	v_fmac_f32_dpp v149, v115, v185 row_ror:2 row_mask:0xf bank_mask:0x1
	v_pk_mul_f32 v[254:255], v[238:239], v[254:255]
	v_pk_mul_f32 v[148:149], v[240:241], v[148:149]
	v_cvt_pk_bf16_f32 v244, v254, v255
	v_cvt_pk_bf16_f32 v245, v148, v149
	s_add_u32 s56, s46, 0x2c000
	s_addc_u32 s57, s47, 0
	global_store_dwordx4 v151, v[242:245], s[56:57]
	v_mov_b32_e32 v220, 0
	v_mov_b32_e32 v221, 0
	v_mov_b32_e32 v222, 0
	v_mov_b32_e32 v223, 0
	v_mov_b32_e32 v116, 0
	v_mov_b32_e32 v117, 0
	v_mov_b32_e32 v118, 0
	v_mov_b32_e32 v119, 0
	v_mov_b32_e32 v84, 0
	v_mov_b32_e32 v85, 0
	v_mov_b32_e32 v86, 0
	v_mov_b32_e32 v87, 0
	v_mov_b32_e32 v100, 0
	v_mov_b32_e32 v101, 0
	v_mov_b32_e32 v102, 0
	v_mov_b32_e32 v103, 0
	v_mov_b32_e32 v68, 0
	v_mov_b32_e32 v69, 0
	v_mov_b32_e32 v70, 0
	v_mov_b32_e32 v71, 0
	s_and_b32 s14, s75, 31
	s_cselect_b64 s[92:93], -1, 0
	v_add_u32_e32 v246, 0x16000, v150
	s_and_b64 vcc, exec, s[86:87]
	s_cbranch_vccnz .Lfe_h0a
	s_mov_b64 s[14:15], exec
	s_mov_b64 exec, s[10:11]
	global_load_dwordx4 v[116:119], v246, s[44:45]
	global_load_dwordx4 v[84:87], v246, s[44:45] offset:16
	global_load_dwordx4 v[100:103], v246, s[44:45] offset:512
	global_load_dwordx4 v[68:71], v246, s[44:45] offset:528
	s_mov_b64 exec, s[14:15]
	s_and_b64 vcc, exec, s[92:93]
	s_cbranch_vccz .Lfe_h0a
	s_mov_b64 s[14:15], exec
	s_mov_b64 exec, s[10:11]
	global_load_dwordx4 v[220:223], v150, s[44:45]
	global_load_dwordx4 v[224:227], v150, s[44:45] offset:16
	global_load_dwordx4 v[228:231], v150, s[44:45] offset:512
	global_load_dwordx4 v[232:235], v150, s[44:45] offset:528
	s_mov_b64 exec, s[14:15]

;     __device__ __forceinline__ void operator()(const f32x4 (&acc)[2][2][4][2], const Unit& u, int wr, int wc, int fr, int fq) const {
;     ...
;         if (!halo_ok) {
;             if (threadIdx.x < 64) { unsigned sp = 0;
;                 while ((unsigned)__builtin_amdgcn_readfirstlane(__hip_atomic_load(halo_ctr, __ATOMIC_RELAXED, __HIP_MEMORY_SCOPE_AGENT)) < halo_need) { __builtin_amdgcn_s_sleep(8); if (++sp > (1u << 20)) break; }
;                 __builtin_amdgcn_fence(__ATOMIC_ACQUIRE, "agent"); asm volatile("s_waitcnt vmcnt(0)" ::: "memory"); }
;             asm volatile("" ::: "memory"); __builtin_amdgcn_s_barrier(); asm volatile("" ::: "memory");
;             halo_ok = 1;
;         }
.Lfe_hw1:
	global_load_dword v247, v169, s[40:41] sc1
	s_mov_b64 s[84:85], -1
	s_waitcnt vmcnt(0)
	v_readfirstlane_b32 s48, v247
	s_cmp_gt_u32 s48, 43
	s_cbranch_scc1 .Lfe_hw0
	s_add_i32 s13, s13, -1
	s_cmp_eq_u32 s13, 0
	s_cselect_b64 s[84:85], -1, 0
	s_sleep 1
	s_branch .Lfe_hw0
